# full stack: v048 + P11 loop back-edge pointer updates hoisted before the closing barrier
# baseline (speedup 1.0000x reference)
; #define PG8_STAGE(bufoff, gbase, voff) do { _Pragma("unroll") for (int _i = 0; _i < 2; ++_i) \
;         __builtin_amdgcn_global_load_lds((const unsigned*)((const char*)(gbase) + (voff)[_i]), (LAS unsigned*)(lds + (bufoff) + ldsw + _i * 8192), 16, 0, 0); } while (0)
; #define PG8_LDA(dst, b, h) do { _Pragma("unroll") for (int m = 0; m < 4; ++m) _Pragma("unroll") for (int k = 0; k < 2; ++k) dst[m][k] = *(const LAS bf16x8*)(lds + PG8_SA(b, h) + aoff + m * 2048 + k * 1024); } while (0)
; #define PG8_LDB(dst, b, h) do { _Pragma("unroll") for (int n = 0; n < 2; ++n) _Pragma("unroll") for (int k = 0; k < 2; ++k) dst[n][k] = *(const LAS bf16x8*)(lds + PG8_SB(b, h) + boff + n * 2048 + k * 1024); } while (0)
; #define PG8_MMA(ai, bj, At, Bt) do { __builtin_amdgcn_s_setprio(1); _Pragma("unroll") for (int m = 0; m < 4; ++m) _Pragma("unroll") for (int n = 0; n < 2; ++n) _Pragma("unroll") for (int k = 0; k < 2; ++k) \
;         acc[ai][bj][m][n] = __builtin_amdgcn_mfma_f32_16x16x32_bf16(Bt[n][k], At[m][k], acc[ai][bj][m][n], 0, 0, 0); __builtin_amdgcn_s_setprio(0); } while (0)
; #define PG8_BAR __builtin_amdgcn_s_barrier()
; template <class Epi, class Sched, bool ALIGN_EPI = false, bool SP2 = false>
; __device__ __forceinline__ void gemm_phase(LAS unsigned char* lds, const Gemm g, const Sched& S, const Epi& E) {
;     ...
;         const bool has_next = S.next(ui + 1, nxt);
;         const char* nA = has_next ? (const char*)g.A + (size_t)nxt.pm * tstepA : cA; const char* nB = has_next ? (const char*)g.Bt + (size_t)nxt.pn * tstepB : cB;
;         for (int t = 0; t < nt; t += 2) {
;             const bool last = (t == nt - 2);
;             const char* a1 = cA + (size_t)(t + 1) * kstep;
;             const char* a2 = last ? nA : cA + (size_t)(t + 2) * kstep; const char* b2 = last ? nB : cB + (size_t)(t + 2) * kstep;
;             const char* a3 = a2 + kstep; const char* b3 = b2 + kstep;
;             if (last && has_next) S.a_ready(nxt);
;             if constexpr (SP2) {
;             PG8_LDB(B0, 0, 0); PG8_LDB(B1, 0, 1); PG8_SCHED; PG8_LDA(At, 0, 0); PG8_STAGE(PG8_SA(1, 1), a1 + hstepA, voffA);
;             PG8_WAIT_V(8); PG8_WAIT_L(0); PG8_BAR; PG8_MMA(0, 0, At, B0); PG8_MMA(0, 1, At, B1); PG8_BAR; PG8_SCHED;
;             PG8_LDA(At, 0, 1); PG8_STAGE(PG8_SB(0, 0), b2, voffB); PG8_STAGE(PG8_SB(0, 1), b2 + hstepB, voffB); PG8_STAGE(PG8_SA(0, 0), a2, voffA);
.LBB0_1138:
	ds_read_b128 v[128:131], v176
	ds_read_b128 v[132:135], v176 offset:1024
	ds_read_b128 v[152:155], v176 offset:2048
	ds_read_b128 v[156:159], v176 offset:3072
	ds_read_b128 v[160:163], v177
	ds_read_b128 v[164:167], v177 offset:1024
	ds_read_b128 v[168:171], v177 offset:2048
	ds_read_b128 v[182:185], v177 offset:3072
	s_add_u32 s22, s20, 0xffea0080
	s_addc_u32 s23, s21, -1
	s_cmpk_eq_i32 s49, 0x54
	s_cselect_b32 s25, s3, s23
	s_cselect_b32 s24, s2, s22
	s_cselect_b32 s23, s19, s48
	s_cselect_b32 s22, s18, s47
	v_lshl_add_u64 v[172:173], s[20:21], 0, v[144:145]
	s_add_i32 m0, s28, 0xc000
	ds_read_b128 v[186:189], v178
	ds_read_b128 v[190:193], v178 offset:1024
	ds_read_b128 v[194:197], v178 offset:2048
	ds_read_b128 v[198:201], v178 offset:3072
	ds_read_b128 v[202:205], v178 offset:4096
	ds_read_b128 v[206:209], v178 offset:5120
	ds_read_b128 v[210:213], v178 offset:6144
	ds_read_b128 v[214:217], v178 offset:7168
	global_load_lds_dwordx4 v[172:173], off
	s_add_i32 m0, s28, 0xe000
	v_lshl_add_u64 v[172:173], s[20:21], 0, v[146:147]
	global_load_lds_dwordx4 v[172:173], off
	s_waitcnt vmcnt(8) lgkmcnt(0)
	s_setprio 1
	s_barrier
	v_mfma_f32_16x16x32_bf16 v[124:127], v[128:131], v[186:189], v[124:127]
	v_mfma_f32_16x16x32_bf16 v[120:123], v[152:155], v[186:189], v[120:123]
	v_mfma_f32_16x16x32_bf16 v[116:119], v[128:131], v[194:197], v[116:119]
	v_mfma_f32_16x16x32_bf16 v[112:115], v[152:155], v[194:197], v[112:115]
	v_mfma_f32_16x16x32_bf16 v[108:111], v[128:131], v[202:205], v[108:111]
	v_mfma_f32_16x16x32_bf16 v[104:107], v[152:155], v[202:205], v[104:107]
	v_mfma_f32_16x16x32_bf16 v[100:103], v[128:131], v[210:213], v[100:103]
	v_mfma_f32_16x16x32_bf16 v[96:99], v[152:155], v[210:213], v[96:99]
	v_mfma_f32_16x16x32_bf16 v[124:127], v[132:135], v[190:193], v[124:127]
	v_mfma_f32_16x16x32_bf16 v[120:123], v[156:159], v[190:193], v[120:123]
	v_mfma_f32_16x16x32_bf16 v[116:119], v[132:135], v[198:201], v[116:119]
	v_mfma_f32_16x16x32_bf16 v[112:115], v[156:159], v[198:201], v[112:115]
	v_mfma_f32_16x16x32_bf16 v[108:111], v[132:135], v[206:209], v[108:111]
	v_mfma_f32_16x16x32_bf16 v[104:107], v[156:159], v[206:209], v[104:107]
	v_mfma_f32_16x16x32_bf16 v[100:103], v[132:135], v[214:217], v[100:103]
	v_mfma_f32_16x16x32_bf16 v[96:99], v[156:159], v[214:217], v[96:99]
	s_setprio 0
	s_setprio 1
	v_mfma_f32_16x16x32_bf16 v[68:71], v[160:163], v[186:189], v[68:71]
	v_mfma_f32_16x16x32_bf16 v[60:63], v[168:171], v[186:189], v[60:63]
	v_mfma_f32_16x16x32_bf16 v[52:55], v[160:163], v[194:197], v[52:55]
	v_mfma_f32_16x16x32_bf16 v[48:51], v[168:171], v[194:197], v[48:51]
	v_mfma_f32_16x16x32_bf16 v[44:47], v[160:163], v[202:205], v[44:47]
	v_mfma_f32_16x16x32_bf16 v[40:43], v[168:171], v[202:205], v[40:43]
	v_mfma_f32_16x16x32_bf16 v[36:39], v[160:163], v[210:213], v[36:39]
	v_mfma_f32_16x16x32_bf16 v[32:35], v[168:171], v[210:213], v[32:35]
	v_mfma_f32_16x16x32_bf16 v[68:71], v[164:167], v[190:193], v[68:71]
	v_mfma_f32_16x16x32_bf16 v[60:63], v[182:185], v[190:193], v[60:63]
	v_mfma_f32_16x16x32_bf16 v[52:55], v[164:167], v[198:201], v[52:55]
	v_mfma_f32_16x16x32_bf16 v[48:51], v[182:185], v[198:201], v[48:51]
	v_mfma_f32_16x16x32_bf16 v[44:47], v[164:167], v[206:209], v[44:47]
	v_mfma_f32_16x16x32_bf16 v[40:43], v[182:185], v[206:209], v[40:43]
	v_mfma_f32_16x16x32_bf16 v[36:39], v[164:167], v[214:217], v[36:39]
	v_mfma_f32_16x16x32_bf16 v[32:35], v[182:185], v[214:217], v[32:35]
	s_setprio 0
	s_barrier
	s_add_i32 s50, s40, s27
	v_lshl_add_u64 v[172:173], s[22:23], 0, v[138:139]
	s_mov_b32 m0, s50
	ds_read_b128 v[186:189], v178 offset:16384
	ds_read_b128 v[190:193], v178 offset:17408
	ds_read_b128 v[194:197], v178 offset:18432
	ds_read_b128 v[198:201], v178 offset:19456
	ds_read_b128 v[202:205], v178 offset:20480
	ds_read_b128 v[206:209], v178 offset:21504
	ds_read_b128 v[210:213], v178 offset:22528
	ds_read_b128 v[214:217], v178 offset:23552
	global_load_lds_dwordx4 v[172:173], off
	s_add_i32 m0, s50, 0x2000
	s_add_u32 s50, s22, 0x160000
	v_lshl_add_u64 v[218:219], s[22:23], 0, v[142:143]
	s_addc_u32 s51, s23, 0
	s_add_i32 s52, s41, s27
	global_load_lds_dwordx4 v[218:219], off
	v_lshl_add_u64 v[220:221], s[50:51], 0, v[138:139]
	s_mov_b32 m0, s52
	v_lshl_add_u64 v[222:223], s[24:25], 0, v[140:141]
	global_load_lds_dwordx4 v[220:221], off
	s_add_i32 m0, s52, 0x2000
	v_lshl_add_u64 v[220:221], s[50:51], 0, v[142:143]
	global_load_lds_dwordx4 v[220:221], off
	s_mov_b32 m0, s28
	v_lshl_add_u64 v[220:221], s[24:25], 0, v[136:137]
	global_load_lds_dwordx4 v[220:221], off
	s_mov_b32 m0, s29
	s_nop 0
	global_load_lds_dwordx4 v[222:223], off
	s_waitcnt vmcnt(8) lgkmcnt(0)
	s_setprio 1
	s_barrier
; #define PG8_STAGE(bufoff, gbase, voff) do { _Pragma("unroll") for (int _i = 0; _i < 2; ++_i) \
;         __builtin_amdgcn_global_load_lds((const unsigned*)((const char*)(gbase) + (voff)[_i]), (LAS unsigned*)(lds + (bufoff) + ldsw + _i * 8192), 16, 0, 0); } while (0)
; #define PG8_LDA(dst, b, h) do { _Pragma("unroll") for (int m = 0; m < 4; ++m) _Pragma("unroll") for (int k = 0; k < 2; ++k) dst[m][k] = *(const LAS bf16x8*)(lds + PG8_SA(b, h) + aoff + m * 2048 + k * 1024); } while (0)
; #define PG8_LDB(dst, b, h) do { _Pragma("unroll") for (int n = 0; n < 2; ++n) _Pragma("unroll") for (int k = 0; k < 2; ++k) dst[n][k] = *(const LAS bf16x8*)(lds + PG8_SB(b, h) + boff + n * 2048 + k * 1024); } while (0)
; #define PG8_MMA(ai, bj, At, Bt) do { __builtin_amdgcn_s_setprio(1); _Pragma("unroll") for (int m = 0; m < 4; ++m) _Pragma("unroll") for (int n = 0; n < 2; ++n) _Pragma("unroll") for (int k = 0; k < 2; ++k) \
;         acc[ai][bj][m][n] = __builtin_amdgcn_mfma_f32_16x16x32_bf16(Bt[n][k], At[m][k], acc[ai][bj][m][n], 0, 0, 0); __builtin_amdgcn_s_setprio(0); } while (0)
; #define PG8_WAIT_V(n) asm volatile("s_waitcnt vmcnt(" #n ")" ::: "memory")
; #define PG8_WAIT_L(n) asm volatile("s_waitcnt lgkmcnt(" #n ")" ::: "memory")
; #define PG8_BAR __builtin_amdgcn_s_barrier()
; #define PG8_SCHED __builtin_amdgcn_sched_barrier(0)
; template <class Epi, class Sched, bool ALIGN_EPI = false, bool SP2 = false>
; __device__ __forceinline__ void gemm_phase(LAS unsigned char* lds, const Gemm g, const Sched& S, const Epi& E) {
;     ...
;             PG8_WAIT_V(8); PG8_WAIT_L(0); PG8_BAR; PG8_MMA(1, 0, At, B0); PG8_MMA(1, 1, At, B1); PG8_BAR; PG8_SCHED;
;             PG8_LDB(B0, 1, 0); PG8_LDB(B1, 1, 1); PG8_SCHED; PG8_LDA(At, 1, 0); PG8_STAGE(PG8_SA(0, 1), a2 + hstepA, voffA);
;             PG8_WAIT_V(8); PG8_WAIT_L(0); PG8_BAR; PG8_MMA(0, 0, At, B0); PG8_MMA(0, 1, At, B1); PG8_BAR; PG8_SCHED;
	v_mfma_f32_16x16x32_bf16 v[92:95], v[128:131], v[186:189], v[92:95]
	v_mfma_f32_16x16x32_bf16 v[88:91], v[152:155], v[186:189], v[88:91]
	v_mfma_f32_16x16x32_bf16 v[84:87], v[128:131], v[194:197], v[84:87]
	v_mfma_f32_16x16x32_bf16 v[80:83], v[152:155], v[194:197], v[80:83]
	v_mfma_f32_16x16x32_bf16 v[76:79], v[128:131], v[202:205], v[76:79]
	v_mfma_f32_16x16x32_bf16 v[72:75], v[152:155], v[202:205], v[72:75]
	v_mfma_f32_16x16x32_bf16 v[64:67], v[128:131], v[210:213], v[64:67]
	v_mfma_f32_16x16x32_bf16 v[56:59], v[152:155], v[210:213], v[56:59]
	v_mfma_f32_16x16x32_bf16 v[92:95], v[132:135], v[190:193], v[92:95]
	v_mfma_f32_16x16x32_bf16 v[88:91], v[156:159], v[190:193], v[88:91]
	v_mfma_f32_16x16x32_bf16 v[84:87], v[132:135], v[198:201], v[84:87]
	v_mfma_f32_16x16x32_bf16 v[80:83], v[156:159], v[198:201], v[80:83]
	v_mfma_f32_16x16x32_bf16 v[76:79], v[132:135], v[206:209], v[76:79]
	v_mfma_f32_16x16x32_bf16 v[72:75], v[156:159], v[206:209], v[72:75]
	v_mfma_f32_16x16x32_bf16 v[64:67], v[132:135], v[214:217], v[64:67]
	v_mfma_f32_16x16x32_bf16 v[56:59], v[156:159], v[214:217], v[56:59]
	s_setprio 0
	s_setprio 1
	v_mfma_f32_16x16x32_bf16 v[28:31], v[160:163], v[186:189], v[28:31]
	v_mfma_f32_16x16x32_bf16 v[24:27], v[168:171], v[186:189], v[24:27]
	v_mfma_f32_16x16x32_bf16 v[20:23], v[160:163], v[194:197], v[20:23]
	v_mfma_f32_16x16x32_bf16 v[16:19], v[168:171], v[194:197], v[16:19]
	v_mfma_f32_16x16x32_bf16 v[12:15], v[160:163], v[202:205], v[12:15]
	v_mfma_f32_16x16x32_bf16 v[8:11], v[168:171], v[202:205], v[8:11]
	v_mfma_f32_16x16x32_bf16 v[4:7], v[160:163], v[210:213], v[4:7]
	v_mfma_f32_16x16x32_bf16 v[0:3], v[168:171], v[210:213], v[0:3]
	v_mfma_f32_16x16x32_bf16 v[28:31], v[164:167], v[190:193], v[28:31]
	v_mfma_f32_16x16x32_bf16 v[24:27], v[182:185], v[190:193], v[24:27]
	v_mfma_f32_16x16x32_bf16 v[20:23], v[164:167], v[198:201], v[20:23]
	v_mfma_f32_16x16x32_bf16 v[16:19], v[182:185], v[198:201], v[16:19]
	v_mfma_f32_16x16x32_bf16 v[12:15], v[164:167], v[206:209], v[12:15]
	v_mfma_f32_16x16x32_bf16 v[8:11], v[182:185], v[206:209], v[8:11]
	v_mfma_f32_16x16x32_bf16 v[4:7], v[164:167], v[214:217], v[4:7]
	v_mfma_f32_16x16x32_bf16 v[0:3], v[182:185], v[214:217], v[0:3]
	s_setprio 0
	s_barrier
	ds_read_b128 v[128:131], v179
	ds_read_b128 v[132:135], v179 offset:1024
	ds_read_b128 v[152:155], v179 offset:2048
	ds_read_b128 v[156:159], v179 offset:3072
	ds_read_b128 v[160:163], v180
	ds_read_b128 v[164:167], v180 offset:1024
	ds_read_b128 v[168:171], v180 offset:2048
	ds_read_b128 v[182:185], v180 offset:3072
	s_add_u32 s24, s24, 0x160000
	s_addc_u32 s25, s25, 0
	s_mov_b32 m0, s30
	v_lshl_add_u64 v[224:225], s[24:25], 0, v[136:137]
	ds_read_b128 v[186:189], v178 offset:32768
	ds_read_b128 v[190:193], v178 offset:33792
	ds_read_b128 v[194:197], v178 offset:34816
	ds_read_b128 v[198:201], v178 offset:35840
	ds_read_b128 v[202:205], v178 offset:36864
	ds_read_b128 v[206:209], v178 offset:37888
	ds_read_b128 v[210:213], v178 offset:38912
	ds_read_b128 v[214:217], v178 offset:39936
	global_load_lds_dwordx4 v[224:225], off
	s_mov_b32 m0, s31
	v_lshl_add_u64 v[224:225], s[24:25], 0, v[140:141]
	global_load_lds_dwordx4 v[224:225], off
	s_waitcnt vmcnt(8) lgkmcnt(0)
	s_setprio 1
	s_barrier
	v_mfma_f32_16x16x32_bf16 v[124:127], v[128:131], v[186:189], v[124:127]
	v_mfma_f32_16x16x32_bf16 v[120:123], v[152:155], v[186:189], v[120:123]
	v_mfma_f32_16x16x32_bf16 v[116:119], v[128:131], v[194:197], v[116:119]
	v_mfma_f32_16x16x32_bf16 v[112:115], v[152:155], v[194:197], v[112:115]
	v_mfma_f32_16x16x32_bf16 v[108:111], v[128:131], v[202:205], v[108:111]
	v_mfma_f32_16x16x32_bf16 v[104:107], v[152:155], v[202:205], v[104:107]
	v_mfma_f32_16x16x32_bf16 v[100:103], v[128:131], v[210:213], v[100:103]
	v_mfma_f32_16x16x32_bf16 v[96:99], v[152:155], v[210:213], v[96:99]
	v_mfma_f32_16x16x32_bf16 v[124:127], v[132:135], v[190:193], v[124:127]
	v_mfma_f32_16x16x32_bf16 v[120:123], v[156:159], v[190:193], v[120:123]
	v_mfma_f32_16x16x32_bf16 v[116:119], v[132:135], v[198:201], v[116:119]
	v_mfma_f32_16x16x32_bf16 v[112:115], v[156:159], v[198:201], v[112:115]
	v_mfma_f32_16x16x32_bf16 v[108:111], v[132:135], v[206:209], v[108:111]
	v_mfma_f32_16x16x32_bf16 v[104:107], v[156:159], v[206:209], v[104:107]
	v_mfma_f32_16x16x32_bf16 v[100:103], v[132:135], v[214:217], v[100:103]
	v_mfma_f32_16x16x32_bf16 v[96:99], v[156:159], v[214:217], v[96:99]
	s_setprio 0
	s_setprio 1
	v_mfma_f32_16x16x32_bf16 v[68:71], v[160:163], v[186:189], v[68:71]
	v_mfma_f32_16x16x32_bf16 v[60:63], v[168:171], v[186:189], v[60:63]
	v_mfma_f32_16x16x32_bf16 v[52:55], v[160:163], v[194:197], v[52:55]
	v_mfma_f32_16x16x32_bf16 v[48:51], v[168:171], v[194:197], v[48:51]
	v_mfma_f32_16x16x32_bf16 v[44:47], v[160:163], v[202:205], v[44:47]
	v_mfma_f32_16x16x32_bf16 v[40:43], v[168:171], v[202:205], v[40:43]
	v_mfma_f32_16x16x32_bf16 v[36:39], v[160:163], v[210:213], v[36:39]
	v_mfma_f32_16x16x32_bf16 v[32:35], v[168:171], v[210:213], v[32:35]
	v_mfma_f32_16x16x32_bf16 v[68:71], v[164:167], v[190:193], v[68:71]
	v_mfma_f32_16x16x32_bf16 v[60:63], v[182:185], v[190:193], v[60:63]
	v_mfma_f32_16x16x32_bf16 v[52:55], v[164:167], v[198:201], v[52:55]
	v_mfma_f32_16x16x32_bf16 v[48:51], v[182:185], v[198:201], v[48:51]
	v_mfma_f32_16x16x32_bf16 v[44:47], v[164:167], v[206:209], v[44:47]
	v_mfma_f32_16x16x32_bf16 v[40:43], v[182:185], v[206:209], v[40:43]
	v_mfma_f32_16x16x32_bf16 v[36:39], v[164:167], v[214:217], v[36:39]
	v_mfma_f32_16x16x32_bf16 v[32:35], v[182:185], v[214:217], v[32:35]
	s_setprio 0
	s_barrier
; #define PG8_STAGE(bufoff, gbase, voff) do { _Pragma("unroll") for (int _i = 0; _i < 2; ++_i) \
;         __builtin_amdgcn_global_load_lds((const unsigned*)((const char*)(gbase) + (voff)[_i]), (LAS unsigned*)(lds + (bufoff) + ldsw + _i * 8192), 16, 0, 0); } while (0)
; #define PG8_LDA(dst, b, h) do { _Pragma("unroll") for (int m = 0; m < 4; ++m) _Pragma("unroll") for (int k = 0; k < 2; ++k) dst[m][k] = *(const LAS bf16x8*)(lds + PG8_SA(b, h) + aoff + m * 2048 + k * 1024); } while (0)
; #define PG8_MMA(ai, bj, At, Bt) do { __builtin_amdgcn_s_setprio(1); _Pragma("unroll") for (int m = 0; m < 4; ++m) _Pragma("unroll") for (int n = 0; n < 2; ++n) _Pragma("unroll") for (int k = 0; k < 2; ++k) \
;         acc[ai][bj][m][n] = __builtin_amdgcn_mfma_f32_16x16x32_bf16(Bt[n][k], At[m][k], acc[ai][bj][m][n], 0, 0, 0); __builtin_amdgcn_s_setprio(0); } while (0)
; #define PG8_WAIT_V(n) asm volatile("s_waitcnt vmcnt(" #n ")" ::: "memory")
; #define PG8_WAIT_L(n) asm volatile("s_waitcnt lgkmcnt(" #n ")" ::: "memory")
; #define PG8_BAR __builtin_amdgcn_s_barrier()
; #define PG8_SCHED __builtin_amdgcn_sched_barrier(0)
; template <class Epi, class Sched, bool ALIGN_EPI = false, bool SP2 = false>
; __device__ __forceinline__ void gemm_phase(LAS unsigned char* lds, const Gemm g, const Sched& S, const Epi& E) {
;     ...
;             PG8_LDA(At, 1, 1); PG8_STAGE(PG8_SB(1, 0), b3, voffB); PG8_STAGE(PG8_SB(1, 1), b3 + hstepB, voffB); PG8_STAGE(PG8_SA(1, 0), a3, voffA);
;             PG8_WAIT_V(8); PG8_WAIT_L(0); PG8_BAR; PG8_MMA(1, 0, At, B0); PG8_MMA(1, 1, At, B1); PG8_BAR; PG8_SCHED;
;     ...
;         if constexpr (ALIGN_EPI) { if (wr == 0) PG8_BAR; }
	s_add_i32 s24, s42, s27
	v_lshl_add_u64 v[172:173], v[172:173], 0, s[8:9]
	s_mov_b32 m0, s24
	ds_read_b128 v[186:189], v178 offset:49152
	ds_read_b128 v[190:193], v178 offset:50176
	ds_read_b128 v[194:197], v178 offset:51200
	ds_read_b128 v[198:201], v178 offset:52224
	ds_read_b128 v[202:205], v178 offset:53248
	ds_read_b128 v[206:209], v178 offset:54272
	ds_read_b128 v[210:213], v178 offset:55296
	ds_read_b128 v[214:217], v178 offset:56320
	global_load_lds_dwordx4 v[172:173], off
	s_add_i32 m0, s24, 0x2000
	s_add_u32 s22, s22, 0x160080
	v_lshl_add_u64 v[172:173], v[218:219], 0, s[8:9]
	s_addc_u32 s23, s23, 0
	s_add_i32 s24, s43, s27
	global_load_lds_dwordx4 v[172:173], off
	s_mov_b32 m0, s24
	v_lshl_add_u64 v[172:173], s[22:23], 0, v[138:139]
	global_load_lds_dwordx4 v[172:173], off
	s_add_i32 m0, s24, 0x2000
	v_lshl_add_u64 v[172:173], s[22:23], 0, v[142:143]
	global_load_lds_dwordx4 v[172:173], off
	s_mov_b32 m0, s36
	v_lshl_add_u64 v[172:173], v[220:221], 0, s[8:9]
	global_load_lds_dwordx4 v[172:173], off
	s_mov_b32 m0, s37
	v_lshl_add_u64 v[172:173], v[222:223], 0, s[8:9]
	global_load_lds_dwordx4 v[172:173], off
	s_waitcnt vmcnt(8) lgkmcnt(0)
	s_setprio 1
	s_barrier
	v_mfma_f32_16x16x32_bf16 v[92:95], v[128:131], v[186:189], v[92:95]
	v_mfma_f32_16x16x32_bf16 v[88:91], v[152:155], v[186:189], v[88:91]
	v_mfma_f32_16x16x32_bf16 v[84:87], v[128:131], v[194:197], v[84:87]
	v_mfma_f32_16x16x32_bf16 v[80:83], v[152:155], v[194:197], v[80:83]
	v_mfma_f32_16x16x32_bf16 v[76:79], v[128:131], v[202:205], v[76:79]
	v_mfma_f32_16x16x32_bf16 v[72:75], v[152:155], v[202:205], v[72:75]
	v_mfma_f32_16x16x32_bf16 v[64:67], v[128:131], v[210:213], v[64:67]
	v_mfma_f32_16x16x32_bf16 v[56:59], v[152:155], v[210:213], v[56:59]
	v_mfma_f32_16x16x32_bf16 v[92:95], v[132:135], v[190:193], v[92:95]
	v_mfma_f32_16x16x32_bf16 v[88:91], v[156:159], v[190:193], v[88:91]
	v_mfma_f32_16x16x32_bf16 v[84:87], v[132:135], v[198:201], v[84:87]
	v_mfma_f32_16x16x32_bf16 v[80:83], v[156:159], v[198:201], v[80:83]
	v_mfma_f32_16x16x32_bf16 v[76:79], v[132:135], v[206:209], v[76:79]
	v_mfma_f32_16x16x32_bf16 v[72:75], v[156:159], v[206:209], v[72:75]
	v_mfma_f32_16x16x32_bf16 v[64:67], v[132:135], v[214:217], v[64:67]
	v_mfma_f32_16x16x32_bf16 v[56:59], v[156:159], v[214:217], v[56:59]
	s_setprio 0
	s_setprio 1
	v_mfma_f32_16x16x32_bf16 v[28:31], v[160:163], v[186:189], v[28:31]
	v_mfma_f32_16x16x32_bf16 v[24:27], v[168:171], v[186:189], v[24:27]
	v_mfma_f32_16x16x32_bf16 v[20:23], v[160:163], v[194:197], v[20:23]
	v_mfma_f32_16x16x32_bf16 v[16:19], v[168:171], v[194:197], v[16:19]
	v_mfma_f32_16x16x32_bf16 v[12:15], v[160:163], v[202:205], v[12:15]
	v_mfma_f32_16x16x32_bf16 v[8:11], v[168:171], v[202:205], v[8:11]
	v_mfma_f32_16x16x32_bf16 v[4:7], v[160:163], v[210:213], v[4:7]
	v_mfma_f32_16x16x32_bf16 v[0:3], v[168:171], v[210:213], v[0:3]
	v_mfma_f32_16x16x32_bf16 v[28:31], v[164:167], v[190:193], v[28:31]
	v_mfma_f32_16x16x32_bf16 v[24:27], v[182:185], v[190:193], v[24:27]
	v_mfma_f32_16x16x32_bf16 v[20:23], v[164:167], v[198:201], v[20:23]
	v_mfma_f32_16x16x32_bf16 v[16:19], v[182:185], v[198:201], v[16:19]
	v_mfma_f32_16x16x32_bf16 v[12:15], v[164:167], v[206:209], v[12:15]
	v_mfma_f32_16x16x32_bf16 v[8:11], v[182:185], v[206:209], v[8:11]
	v_mfma_f32_16x16x32_bf16 v[4:7], v[164:167], v[214:217], v[4:7]
	v_mfma_f32_16x16x32_bf16 v[0:3], v[182:185], v[214:217], v[0:3]
	s_add_i32 s49, s49, 2
	s_add_u32 s20, s20, 0x100
	s_addc_u32 s21, s21, 0
	s_add_u32 s47, s47, 0x100
	s_addc_u32 s48, s48, 0
	s_setprio 0
	s_barrier
	s_cmpk_gt_u32 s49, 0x55
	s_cbranch_scc0 .LBB0_1138
	s_and_b64 vcc, exec, s[10:11]
	s_cbranch_vccz .LBB0_1141
	s_barrier
